# S5 item BT3 stage: Toeplitz pieces read with two predicated ds_read_b128 instead of eight predicated ds_read_b32
# speedup vs baseline: 1.0050x; 1.0004x over previous
.Lssa_495:
	s_andn2_saveexec_b64 s[4:5], s[4:5]
	s_cbranch_execz .Lssa_492
	v_lshrrev_b32_e32 v6, 1, v51
	v_and_b32_e32 v7, 8, v4
	v_sub_co_u32_e32 v6, vcc, v52, v6
	v_lshl_add_u32 v6, v6, 10, 0
	v_lshlrev_b32_e32 v8, 6, v53
	v_lshlrev_b32_e32 v7, 2, v7
	s_xor_b64 s[82:83], vcc, -1
	v_add3_u32 v51, v6, v8, v7
	v_mov_b32_e32 v6, 0
	v_mov_b32_e32 v7, 0
	v_mov_b32_e32 v8, 0
	v_mov_b32_e32 v37, 0
	v_mov_b32_e32 v44, 0
	v_mov_b32_e32 v48, 0
	v_mov_b32_e32 v49, 0
	v_mov_b32_e32 v50, 0
	s_and_saveexec_b64 s[84:85], s[82:83]
	s_cbranch_execz .Lssa_491
	ds_read_b128 v[52:55], v51 offset:25088
	ds_read_b128 v[56:59], v51 offset:25104
	s_waitcnt lgkmcnt(0)
	v_mov_b32_e32 v7, v52
	v_mov_b32_e32 v6, v53
	v_mov_b32_e32 v37, v54
	v_mov_b32_e32 v8, v55
	v_mov_b32_e32 v48, v56
	v_mov_b32_e32 v44, v57
	v_mov_b32_e32 v49, v58
	v_mov_b32_e32 v50, v59
	s_branch .Lssa_491
